# baseline (speedup 1.0000x reference)
.LBB0_48:
	s_or_b64 exec, exec, s[8:9]
	v_cvt_f32_u32_e32 v3, v4
	s_waitcnt vmcnt(0)
	v_readfirstlane_b32 s7, v2
	v_sub_u32_e32 v2, 0, v4
	s_add_u32 s6, s4, 0x1b803500
	v_rcp_iflag_f32_e32 v3, v3
	v_add_u32_e32 v1, s7, v1
	v_add_u32_e32 v5, 1, v1
	s_addc_u32 s7, s5, 0
	v_mul_f32_e32 v3, 0x4f7ffffe, v3
	v_cvt_u32_f32_e32 v3, v3
	s_mov_b64 s[10:11], -1
	v_mul_lo_u32 v2, v2, v3
	v_mul_hi_u32 v2, v3, v2
	v_add_u32_e32 v2, v3, v2
	v_mul_hi_u32 v2, v1, v2
	v_mul_lo_u32 v3, v2, v4
	v_sub_u32_e32 v1, v1, v3
	v_add_u32_e32 v6, 1, v2
	v_sub_u32_e32 v3, v1, v4
	v_cmp_ge_u32_e32 vcc, v1, v4
	s_nop 1
	v_cndmask_b32_e32 v2, v2, v6, vcc
	v_cndmask_b32_e32 v1, v1, v3, vcc
	v_add_u32_e32 v3, 1, v2
	v_cmp_ge_u32_e32 vcc, v1, v4
	s_nop 1
	v_cndmask_b32_e32 v1, v2, v3, vcc
	v_mul_lo_u32 v2, v4, v1
	v_add_u32_e32 v2, v2, v4
	v_cmp_ne_u32_e32 vcc, v5, v2
	v_mov_b64_e32 v[2:3], s[6:7]
	s_nop 0
	s_andn2_b64 s[28:29], exec, vcc
	s_and_saveexec_b64 s[8:9], vcc
	s_cbranch_execz .LBB0_60
	global_load_dword v2, v0, s[6:7] sc1
	s_mov_b64 s[14:15], 0
	s_waitcnt vmcnt(0)
	v_cmp_eq_u32_e32 vcc, v2, v1
	s_and_saveexec_b64 s[12:13], vcc
	s_cbranch_execz .LBB0_59
	s_add_u32 s10, s4, 0x1b800200
	s_addc_u32 s11, s5, 0
	s_mov_b32 s22, 1
	s_mov_b64 s[4:5], 0
	s_branch .LBB0_52

.LBB0_60:
	s_or_b64 exec, exec, s[8:9]
	s_and_saveexec_b64 s[4:5], s[10:11]
	s_cbranch_execz .LBB0_62
	global_atomic_add v[2:3], v207, off
	s_and_b64 s[30:31], s[28:29], exec
	s_cbranch_scc0 .Lbar_nobc
	s_add_u32 s30, s24, 0x2800
	s_addc_u32 s31, s25, 0
	global_atomic_add v0, v207, s[30:31] offset:-1024
	global_atomic_add v0, v207, s[30:31] offset:-768
	global_atomic_add v0, v207, s[30:31] offset:-512
	global_atomic_add v0, v207, s[30:31] offset:-256
	global_atomic_add v0, v207, s[30:31] offset:0
	global_atomic_add v0, v207, s[30:31] offset:256
	global_atomic_add v0, v207, s[30:31] offset:512
	global_atomic_add v0, v207, s[30:31] offset:768
.Lbar_nobc:
.LBB0_62:
	s_or_b64 exec, exec, s[4:5]
	s_mov_b64 s[4:5], exec
	v_mbcnt_lo_u32_b32 v1, s4, 0
	v_mbcnt_hi_u32_b32 v1, s5, v1
	v_cmp_eq_u32_e32 vcc, 0, v1
	s_waitcnt vmcnt(0)
	buffer_inv sc1
	s_and_saveexec_b64 s[6:7], vcc
	s_cbranch_execz .LBB0_64
	s_add_i32 s74, s26, 0x900
	s_lshl_b64 s[8:9], s[74:75], 2
	s_add_u32 s8, s24, s8
	s_addc_u32 s9, s25, s9
	s_bcnt1_i32_b64 s4, s[4:5]
	v_mov_b32_e32 v1, s4
